# v59 + P6 tile-boundary overlap: accumulator zeroing moved into the EpiLN epilogue (header zero block only for the first tile) + first-iteration vmcnt(8) bypass
# baseline (speedup 1.0000x reference)
; #define PG8_STAGE(bufoff, gbase, voff) do { _Pragma("unroll") for (int _i = 0; _i < 2; ++_i) \
;         __builtin_amdgcn_global_load_lds((const unsigned*)((const char*)(gbase) + (voff)[_i]), (PG8_LAS unsigned*)(lds + (bufoff) + ldsw + _i * 8192), 16, 0, 0); } while (0)
; #define PG8_LDA(dst, b, h) do { _Pragma("unroll") for (int m = 0; m < 4; ++m) _Pragma("unroll") for (int k = 0; k < 2; ++k) dst[m][k] = *(const PG8_LAS bf16x8*)(lds + PG8_SA(b, h) + aoff + m * 2048 + k * 1024); } while (0)
; #define PG8_LDB(dst, b, h) do { _Pragma("unroll") for (int n = 0; n < 2; ++n) _Pragma("unroll") for (int k = 0; k < 2; ++k) dst[n][k] = *(const PG8_LAS bf16x8*)(lds + PG8_SB(b, h) + boff + n * 2048 + k * 1024); } while (0)
; #define PG8_SCHED __builtin_amdgcn_sched_barrier(0)
; template <class Epi, class Sched, bool ALIGN_EPI = false, bool SP2 = false>
; __device__ __forceinline__ void gemm_phase(PG8_LAS unsigned char* lds, const Gemm g, const Sched& S, const Epi& E) {
;     ...
;         const char* nA = has_next ? (const char*)((Epi::MULTI && nxt.part) ? g.A2 : g.A) + (size_t)nxt.pm * tstepA : cA; const char* nB = has_next ? (const char*)((Epi::MULTI && nxt.part) ? g.Bt2 : g.Bt) + (size_t)nxt.pn * tstepB : cB;
;         for (int t = 0; t < nt; t += 2) {
;             const bool last = (t == nt - 2);
;             const char* a1 = cA + (size_t)(t + 1) * kstep;
;             const char* a2 = last ? nA : cA + (size_t)(t + 2) * kstep; const char* b2 = last ? nB : cB + (size_t)(t + 2) * kstep;
;             const char* a3 = a2 + kstep; const char* b3 = b2 + kstep;
;             if (last && has_next) S.a_ready(nxt);
;             if constexpr (SP2) {
;             PG8_LDB(B0, 0, 0); PG8_LDB(B1, 0, 1); PG8_SCHED; PG8_LDA(At, 0, 0); PG8_STAGE(PG8_SA(1, 1), a1 + hstepA, voffA);
;     ...
;         if (!keep_acc_)
; #pragma unroll
;         for (int a = 0; a < 2; ++a)
; #pragma unroll
;             for (int b = 0; b < 2; ++b)
; #pragma unroll
;                 for (int m = 0; m < 4; ++m)
; #pragma unroll
;                     for (int n = 0; n < 2; ++n) acc[a][b][m][n] = (f32x4){0.f, 0.f, 0.f, 0.f};
;         cur = nxt; cA = nA; cB = nB; ++ui;
.LBB0_814:
	s_ashr_i32 s43, s42, 31
	s_lshl_b64 s[44:45], s[42:43], 19
	s_add_u32 s44, s64, s44
	s_addc_u32 s45, s65, s45
	s_and_b64 s[48:49], s[40:41], exec
	s_cselect_b32 s43, s45, s35
	s_cselect_b32 s83, s44, s34
	s_ashr_i32 s39, s38, 31
	s_lshl_b64 s[48:49], s[38:39], 19
	s_add_u32 s48, s36, s48
	s_addc_u32 s49, s52, s49
	s_and_b64 s[50:51], s[40:41], exec
	s_cselect_b32 s39, s49, s25
	s_cselect_b32 s89, s48, s24
	s_add_u32 s50, s34, 0x40080
	s_addc_u32 s51, s35, 0
	s_add_u32 s90, s24, 0x100
	v_mov_b32_e32 v2, 0
	s_addc_u32 s91, s25, 0
	s_mov_b32 s76, -2
	v_mov_b32_e32 v3, v2
	s_cmp_gt_u32 s80, 1
	s_cbranch_scc1 .Lp6_zskip
	v_mov_b32_e32 v4, v2
	v_mov_b32_e32 v5, v2
	v_mov_b32_e32 v6, v2
	v_mov_b32_e32 v7, v2
	v_mov_b32_e32 v8, v2
	v_mov_b32_e32 v9, v2
	v_mov_b32_e32 v18, v2
	v_mov_b32_e32 v19, v2
	v_mov_b32_e32 v20, v2
	v_mov_b32_e32 v21, v2
	v_mov_b32_e32 v22, v2
	v_mov_b32_e32 v23, v2
	v_mov_b32_e32 v24, v2
	v_mov_b32_e32 v25, v2
	v_mov_b32_e32 v34, v2
	v_mov_b32_e32 v35, v2
	v_mov_b32_e32 v36, v2
	v_mov_b32_e32 v37, v2
	v_mov_b32_e32 v38, v2
	v_mov_b32_e32 v39, v2
	v_mov_b32_e32 v40, v2
	v_mov_b32_e32 v41, v2
	v_mov_b32_e32 v50, v2
	v_mov_b32_e32 v51, v2
	v_mov_b32_e32 v52, v2
	v_mov_b32_e32 v53, v2
	v_mov_b32_e32 v54, v2
	v_mov_b32_e32 v55, v2
	v_mov_b32_e32 v56, v2
	v_mov_b32_e32 v57, v2
	v_mov_b32_e32 v10, v2
	v_mov_b32_e32 v11, v2
	v_mov_b32_e32 v12, v2
	v_mov_b32_e32 v13, v2
	v_mov_b32_e32 v14, v2
	v_mov_b32_e32 v15, v2
	v_mov_b32_e32 v16, v2
	v_mov_b32_e32 v17, v2
	v_mov_b32_e32 v26, v2
	v_mov_b32_e32 v27, v2
	v_mov_b32_e32 v28, v2
	v_mov_b32_e32 v29, v2
	v_mov_b32_e32 v30, v2
	v_mov_b32_e32 v31, v2
	v_mov_b32_e32 v32, v2
	v_mov_b32_e32 v33, v2
	v_mov_b32_e32 v42, v2
	v_mov_b32_e32 v43, v2
	v_mov_b32_e32 v44, v2
	v_mov_b32_e32 v45, v2
	v_mov_b32_e32 v46, v2
	v_mov_b32_e32 v47, v2
	v_mov_b32_e32 v48, v2
	v_mov_b32_e32 v49, v2
	v_mov_b32_e32 v58, v2
	v_mov_b32_e32 v59, v2
	v_mov_b32_e32 v60, v2
	v_mov_b32_e32 v61, v2
	v_mov_b32_e32 v62, v2
	v_mov_b32_e32 v63, v2
	v_mov_b32_e32 v64, v2
	v_mov_b32_e32 v65, v2
	v_mov_b32_e32 v66, v2
	v_mov_b32_e32 v67, v2
	v_mov_b32_e32 v68, v2
	v_mov_b32_e32 v69, v2
	v_mov_b32_e32 v70, v2
	v_mov_b32_e32 v71, v2
	v_mov_b32_e32 v72, v2
	v_mov_b32_e32 v73, v2
	v_mov_b32_e32 v82, v2
	v_mov_b32_e32 v83, v2
	v_mov_b32_e32 v84, v2
	v_mov_b32_e32 v85, v2
	v_mov_b32_e32 v86, v2
	v_mov_b32_e32 v87, v2
	v_mov_b32_e32 v88, v2
	v_mov_b32_e32 v89, v2
	v_mov_b32_e32 v98, v2
	v_mov_b32_e32 v99, v2
	v_mov_b32_e32 v100, v2
	v_mov_b32_e32 v101, v2
	v_mov_b32_e32 v102, v2
	v_mov_b32_e32 v103, v2
	v_mov_b32_e32 v104, v2
	v_mov_b32_e32 v105, v2
	v_mov_b32_e32 v106, v2
	v_mov_b32_e32 v107, v2
	v_mov_b32_e32 v108, v2
	v_mov_b32_e32 v109, v2
	v_mov_b32_e32 v110, v2
	v_mov_b32_e32 v111, v2
	v_mov_b32_e32 v112, v2
	v_mov_b32_e32 v113, v2
	v_mov_b32_e32 v74, v2
	v_mov_b32_e32 v75, v2
	v_mov_b32_e32 v76, v2
	v_mov_b32_e32 v77, v2
	v_mov_b32_e32 v78, v2
	v_mov_b32_e32 v79, v2
	v_mov_b32_e32 v80, v2
	v_mov_b32_e32 v81, v2
	v_mov_b32_e32 v90, v2
	v_mov_b32_e32 v91, v2
	v_mov_b32_e32 v92, v2
	v_mov_b32_e32 v93, v2
	v_mov_b32_e32 v94, v2
	v_mov_b32_e32 v95, v2
	v_mov_b32_e32 v96, v2
	v_mov_b32_e32 v97, v2
	v_mov_b32_e32 v114, v2
	v_mov_b32_e32 v115, v2
	v_mov_b32_e32 v116, v2
	v_mov_b32_e32 v117, v2
	v_mov_b32_e32 v118, v2
	v_mov_b32_e32 v119, v2
	v_mov_b32_e32 v120, v2
	v_mov_b32_e32 v121, v2
	v_mov_b32_e32 v122, v2
	v_mov_b32_e32 v123, v2
	v_mov_b32_e32 v124, v2
	v_mov_b32_e32 v125, v2
	v_mov_b32_e32 v126, v2
	v_mov_b32_e32 v127, v2
	v_mov_b32_e32 v128, v2
	v_mov_b32_e32 v129, v2
.Lp6_zskip:
.LBB0_815:
	s_add_u32 s4, s50, 0xfffc0080
	s_addc_u32 s5, s51, -1
	s_add_i32 s77, 0, 0x10000
	s_cmp_eq_u32 s76, 12
	s_cselect_b32 s35, s43, s5
	s_cselect_b32 s34, s83, s4
	s_cselect_b32 s25, s39, s91
	s_cselect_b32 s24, s89, s90
	s_add_i32 s4, 0, 0x14000
	v_add_u32_e32 v142, s77, v200
	v_add_u32_e32 v158, s4, v200
	ds_read_b128 v[130:133], v142
	ds_read_b128 v[134:137], v142 offset:1024
	ds_read_b128 v[138:141], v142 offset:2048
	ds_read_b128 v[142:145], v142 offset:3072
	ds_read_b128 v[146:149], v158
	ds_read_b128 v[150:153], v158 offset:1024
	ds_read_b128 v[154:157], v158 offset:2048
	ds_read_b128 v[158:161], v158 offset:3072
	v_lshl_add_u64 v[178:179], s[50:51], 0, v[170:171]
	s_add_i32 m0, s60, 0xc000
	ds_read_b128 v[174:177], v202
	ds_read_b128 v[186:189], v202 offset:1024
	ds_read_b128 v[190:193], v202 offset:2048
	ds_read_b128 v[194:197], v202 offset:3072
	ds_read_b128 v[204:207], v202 offset:4096
	ds_read_b128 v[208:211], v202 offset:5120
	ds_read_b128 v[212:215], v202 offset:6144
	ds_read_b128 v[216:219], v202 offset:7168
	global_load_lds_dwordx4 v[178:179], off
	v_lshl_add_u64 v[178:179], s[50:51], 0, v[172:173]
	s_add_i32 m0, s60, 0xe000
	s_nop 0
	global_load_lds_dwordx4 v[178:179], off
	s_cmp_lg_u32 s76, -2
	s_cbranch_scc1 .Lp6_wait_0
	s_cmp_lt_u32 s80, 2
	s_cbranch_scc0 .Lp6_skip_0

; #define PG8_STAGE(bufoff, gbase, voff) do { _Pragma("unroll") for (int _i = 0; _i < 2; ++_i) \
;         __builtin_amdgcn_global_load_lds((const unsigned*)((const char*)(gbase) + (voff)[_i]), (PG8_LAS unsigned*)(lds + (bufoff) + ldsw + _i * 8192), 16, 0, 0); } while (0)
; #define PG8_LDA(dst, b, h) do { _Pragma("unroll") for (int m = 0; m < 4; ++m) _Pragma("unroll") for (int k = 0; k < 2; ++k) dst[m][k] = *(const PG8_LAS bf16x8*)(lds + PG8_SA(b, h) + aoff + m * 2048 + k * 1024); } while (0)
; #define PG8_LDB(dst, b, h) do { _Pragma("unroll") for (int n = 0; n < 2; ++n) _Pragma("unroll") for (int k = 0; k < 2; ++k) dst[n][k] = *(const PG8_LAS bf16x8*)(lds + PG8_SB(b, h) + boff + n * 2048 + k * 1024); } while (0)
; #define PG8_MMA(ai, bj, At, Bt) do { __builtin_amdgcn_s_setprio(1); _Pragma("unroll") for (int m = 0; m < 4; ++m) _Pragma("unroll") for (int n = 0; n < 2; ++n) _Pragma("unroll") for (int k = 0; k < 2; ++k) \
;         acc[ai][bj][m][n] = __builtin_amdgcn_mfma_f32_16x16x32_bf16(Bt[n][k], At[m][k], acc[ai][bj][m][n], 0, 0, 0); __builtin_amdgcn_s_setprio(0); } while (0)
; #define PG8_WAIT_V(n) asm volatile("s_waitcnt vmcnt(" #n ")" ::: "memory")
; #define PG8_WAIT_L(n) asm volatile("s_waitcnt lgkmcnt(" #n ")" ::: "memory")
; #define PG8_BAR __builtin_amdgcn_s_barrier()
; #define PG8_SCHED __builtin_amdgcn_sched_barrier(0)
; template <class Epi, class Sched, bool ALIGN_EPI = false, bool SP2 = false>
; __device__ __forceinline__ void gemm_phase(PG8_LAS unsigned char* lds, const Gemm g, const Sched& S, const Epi& E) {
;     ...
;             PG8_LDB(B0, 0, 0); PG8_LDB(B1, 0, 1); PG8_SCHED; PG8_LDA(At, 0, 0); PG8_STAGE(PG8_SA(1, 1), a1 + hstepA, voffA);
;             PG8_WAIT_V(8); PG8_WAIT_L(0); PG8_BAR; PG8_MMA(0, 0, At, B0); PG8_MMA(0, 1, At, B1); PG8_BAR; PG8_SCHED;
;             PG8_LDA(At, 0, 1); PG8_STAGE(PG8_SB(0, 0), b2, voffB); PG8_STAGE(PG8_SB(0, 1), b2 + hstepB, voffB); PG8_STAGE(PG8_SA(0, 0), a2, voffA);
.Lp6_skip_0:
	s_waitcnt lgkmcnt(0)
	s_barrier
	s_setprio 1
	s_waitcnt lgkmcnt(0)
	v_mfma_f32_16x16x32_bf16 v[126:129], v[130:133], v[174:177], v[126:129]
	v_mfma_f32_16x16x32_bf16 v[122:125], v[138:141], v[174:177], v[122:125]
	v_mfma_f32_16x16x32_bf16 v[118:121], v[130:133], v[190:193], v[118:121]
	v_mfma_f32_16x16x32_bf16 v[114:117], v[138:141], v[190:193], v[114:117]
	v_mfma_f32_16x16x32_bf16 v[94:97], v[130:133], v[204:207], v[94:97]
	v_mfma_f32_16x16x32_bf16 v[90:93], v[138:141], v[204:207], v[90:93]
	v_mfma_f32_16x16x32_bf16 v[78:81], v[130:133], v[212:215], v[78:81]
	v_mfma_f32_16x16x32_bf16 v[74:77], v[138:141], v[212:215], v[74:77]
	v_mfma_f32_16x16x32_bf16 v[126:129], v[134:137], v[186:189], v[126:129]
	v_mfma_f32_16x16x32_bf16 v[122:125], v[142:145], v[186:189], v[122:125]
	v_mfma_f32_16x16x32_bf16 v[118:121], v[134:137], v[194:197], v[118:121]
	v_mfma_f32_16x16x32_bf16 v[114:117], v[142:145], v[194:197], v[114:117]
	v_mfma_f32_16x16x32_bf16 v[94:97], v[134:137], v[208:211], v[94:97]
	v_mfma_f32_16x16x32_bf16 v[90:93], v[142:145], v[208:211], v[90:93]
	v_mfma_f32_16x16x32_bf16 v[78:81], v[134:137], v[216:219], v[78:81]
	v_mfma_f32_16x16x32_bf16 v[74:77], v[142:145], v[216:219], v[74:77]
	v_mfma_f32_16x16x32_bf16 v[110:113], v[146:149], v[174:177], v[110:113]
	v_mfma_f32_16x16x32_bf16 v[106:109], v[154:157], v[174:177], v[106:109]
	v_mfma_f32_16x16x32_bf16 v[102:105], v[146:149], v[190:193], v[102:105]
	v_mfma_f32_16x16x32_bf16 v[98:101], v[154:157], v[190:193], v[98:101]
	v_mfma_f32_16x16x32_bf16 v[86:89], v[146:149], v[204:207], v[86:89]
	v_mfma_f32_16x16x32_bf16 v[82:85], v[154:157], v[204:207], v[82:85]
	v_mfma_f32_16x16x32_bf16 v[70:73], v[146:149], v[212:215], v[70:73]
	v_mfma_f32_16x16x32_bf16 v[66:69], v[154:157], v[212:215], v[66:69]
	v_mfma_f32_16x16x32_bf16 v[110:113], v[150:153], v[186:189], v[110:113]
	v_mfma_f32_16x16x32_bf16 v[106:109], v[158:161], v[186:189], v[106:109]
	v_mfma_f32_16x16x32_bf16 v[102:105], v[150:153], v[194:197], v[102:105]
	v_mfma_f32_16x16x32_bf16 v[98:101], v[158:161], v[194:197], v[98:101]
	v_mfma_f32_16x16x32_bf16 v[86:89], v[150:153], v[208:211], v[86:89]
	v_mfma_f32_16x16x32_bf16 v[82:85], v[158:161], v[208:211], v[82:85]
	v_mfma_f32_16x16x32_bf16 v[70:73], v[150:153], v[216:219], v[70:73]
	v_mfma_f32_16x16x32_bf16 v[66:69], v[158:161], v[216:219], v[66:69]
	s_setprio 0
	s_barrier
	s_add_i32 s5, s77, s53
	v_lshl_add_u64 v[178:179], s[24:25], 0, v[166:167]
	s_mov_b32 m0, s5
	ds_read_b128 v[174:177], v202 offset:16384
	ds_read_b128 v[186:189], v202 offset:17408
	ds_read_b128 v[190:193], v202 offset:18432
	ds_read_b128 v[194:197], v202 offset:19456
	ds_read_b128 v[204:207], v202 offset:20480
	ds_read_b128 v[208:211], v202 offset:21504
	ds_read_b128 v[212:215], v202 offset:22528
	ds_read_b128 v[216:219], v202 offset:23552
	global_load_lds_dwordx4 v[178:179], off
	s_add_i32 m0, s5, 0x2000
	s_add_u32 s78, s24, 0x40000
	v_lshl_add_u64 v[198:199], s[24:25], 0, v[162:163]
	s_addc_u32 s79, s25, 0
	s_add_i32 s4, s4, s53
	global_load_lds_dwordx4 v[198:199], off
	v_lshl_add_u64 v[220:221], s[78:79], 0, v[166:167]
	s_mov_b32 m0, s4
	v_lshl_add_u64 v[234:235], s[34:35], 0, v[164:165]
	global_load_lds_dwordx4 v[220:221], off
	v_lshl_add_u64 v[220:221], s[78:79], 0, v[162:163]
	s_add_i32 m0, s4, 0x2000
	s_nop 0
	global_load_lds_dwordx4 v[220:221], off
	v_lshl_add_u64 v[220:221], s[34:35], 0, v[168:169]
	s_mov_b32 m0, s60
	s_nop 0
	global_load_lds_dwordx4 v[220:221], off
	s_mov_b32 m0, s61
	s_nop 0
	global_load_lds_dwordx4 v[234:235], off
	s_cmp_lg_u32 s76, -2
	s_cbranch_scc1 .Lp6_wait_1
	s_cmp_lt_u32 s80, 2
	s_cbranch_scc0 .Lp6_skip_1

; #define PG8_STAGE(bufoff, gbase, voff) do { _Pragma("unroll") for (int _i = 0; _i < 2; ++_i) \
;         __builtin_amdgcn_global_load_lds((const unsigned*)((const char*)(gbase) + (voff)[_i]), (PG8_LAS unsigned*)(lds + (bufoff) + ldsw + _i * 8192), 16, 0, 0); } while (0)
; #define PG8_LDA(dst, b, h) do { _Pragma("unroll") for (int m = 0; m < 4; ++m) _Pragma("unroll") for (int k = 0; k < 2; ++k) dst[m][k] = *(const PG8_LAS bf16x8*)(lds + PG8_SA(b, h) + aoff + m * 2048 + k * 1024); } while (0)
; #define PG8_LDB(dst, b, h) do { _Pragma("unroll") for (int n = 0; n < 2; ++n) _Pragma("unroll") for (int k = 0; k < 2; ++k) dst[n][k] = *(const PG8_LAS bf16x8*)(lds + PG8_SB(b, h) + boff + n * 2048 + k * 1024); } while (0)
; #define PG8_MMA(ai, bj, At, Bt) do { __builtin_amdgcn_s_setprio(1); _Pragma("unroll") for (int m = 0; m < 4; ++m) _Pragma("unroll") for (int n = 0; n < 2; ++n) _Pragma("unroll") for (int k = 0; k < 2; ++k) \
;         acc[ai][bj][m][n] = __builtin_amdgcn_mfma_f32_16x16x32_bf16(Bt[n][k], At[m][k], acc[ai][bj][m][n], 0, 0, 0); __builtin_amdgcn_s_setprio(0); } while (0)
; #define PG8_WAIT_V(n) asm volatile("s_waitcnt vmcnt(" #n ")" ::: "memory")
; #define PG8_WAIT_L(n) asm volatile("s_waitcnt lgkmcnt(" #n ")" ::: "memory")
; #define PG8_BAR __builtin_amdgcn_s_barrier()
; #define PG8_SCHED __builtin_amdgcn_sched_barrier(0)
; template <class Epi, class Sched, bool ALIGN_EPI = false, bool SP2 = false>
; __device__ __forceinline__ void gemm_phase(PG8_LAS unsigned char* lds, const Gemm g, const Sched& S, const Epi& E) {
;     ...
;             PG8_WAIT_V(8); PG8_WAIT_L(0); PG8_BAR; PG8_MMA(1, 0, At, B0); PG8_MMA(1, 1, At, B1); PG8_BAR; PG8_SCHED;
;             PG8_LDB(B0, 1, 0); PG8_LDB(B1, 1, 1); PG8_SCHED; PG8_LDA(At, 1, 0); PG8_STAGE(PG8_SA(0, 1), a2 + hstepA, voffA);
;             PG8_WAIT_V(8); PG8_WAIT_L(0); PG8_BAR; PG8_MMA(0, 0, At, B0); PG8_MMA(0, 1, At, B1); PG8_BAR; PG8_SCHED;
.Lp6_skip_1:
	s_waitcnt lgkmcnt(0)
	s_barrier
	s_setprio 1
	s_waitcnt lgkmcnt(0)
	v_mfma_f32_16x16x32_bf16 v[62:65], v[130:133], v[174:177], v[62:65]
	v_mfma_f32_16x16x32_bf16 v[58:61], v[138:141], v[174:177], v[58:61]
	v_mfma_f32_16x16x32_bf16 v[46:49], v[130:133], v[190:193], v[46:49]
	v_mfma_f32_16x16x32_bf16 v[42:45], v[138:141], v[190:193], v[42:45]
	v_mfma_f32_16x16x32_bf16 v[30:33], v[130:133], v[204:207], v[30:33]
	v_mfma_f32_16x16x32_bf16 v[26:29], v[138:141], v[204:207], v[26:29]
	v_mfma_f32_16x16x32_bf16 v[14:17], v[130:133], v[212:215], v[14:17]
	v_mfma_f32_16x16x32_bf16 v[10:13], v[138:141], v[212:215], v[10:13]
	v_mfma_f32_16x16x32_bf16 v[62:65], v[134:137], v[186:189], v[62:65]
	v_mfma_f32_16x16x32_bf16 v[58:61], v[142:145], v[186:189], v[58:61]
	v_mfma_f32_16x16x32_bf16 v[46:49], v[134:137], v[194:197], v[46:49]
	v_mfma_f32_16x16x32_bf16 v[42:45], v[142:145], v[194:197], v[42:45]
	v_mfma_f32_16x16x32_bf16 v[30:33], v[134:137], v[208:211], v[30:33]
	v_mfma_f32_16x16x32_bf16 v[26:29], v[142:145], v[208:211], v[26:29]
	v_mfma_f32_16x16x32_bf16 v[14:17], v[134:137], v[216:219], v[14:17]
	v_mfma_f32_16x16x32_bf16 v[10:13], v[142:145], v[216:219], v[10:13]
	v_mfma_f32_16x16x32_bf16 v[54:57], v[146:149], v[174:177], v[54:57]
	v_mfma_f32_16x16x32_bf16 v[50:53], v[154:157], v[174:177], v[50:53]
	v_mfma_f32_16x16x32_bf16 v[38:41], v[146:149], v[190:193], v[38:41]
	v_mfma_f32_16x16x32_bf16 v[34:37], v[154:157], v[190:193], v[34:37]
	v_mfma_f32_16x16x32_bf16 v[22:25], v[146:149], v[204:207], v[22:25]
	v_mfma_f32_16x16x32_bf16 v[18:21], v[154:157], v[204:207], v[18:21]
	v_mfma_f32_16x16x32_bf16 v[6:9], v[146:149], v[212:215], v[6:9]
	v_mfma_f32_16x16x32_bf16 v[2:5], v[154:157], v[212:215], v[2:5]
	v_mfma_f32_16x16x32_bf16 v[54:57], v[150:153], v[186:189], v[54:57]
	v_mfma_f32_16x16x32_bf16 v[50:53], v[158:161], v[186:189], v[50:53]
	v_mfma_f32_16x16x32_bf16 v[38:41], v[150:153], v[194:197], v[38:41]
	v_mfma_f32_16x16x32_bf16 v[34:37], v[158:161], v[194:197], v[34:37]
	v_mfma_f32_16x16x32_bf16 v[22:25], v[150:153], v[208:211], v[22:25]
	v_mfma_f32_16x16x32_bf16 v[18:21], v[158:161], v[208:211], v[18:21]
	v_mfma_f32_16x16x32_bf16 v[6:9], v[150:153], v[216:219], v[6:9]
	v_mfma_f32_16x16x32_bf16 v[2:5], v[158:161], v[216:219], v[2:5]
	s_setprio 0
	s_barrier
	s_add_i32 s4, 0, 0x18000
	s_add_i32 s5, 0, 0x1c000
	v_add_u32_e32 v142, s4, v200
	v_add_u32_e32 v158, s5, v200
	ds_read_b128 v[130:133], v142
	ds_read_b128 v[134:137], v142 offset:1024
	ds_read_b128 v[138:141], v142 offset:2048
	ds_read_b128 v[142:145], v142 offset:3072
	ds_read_b128 v[146:149], v158
	ds_read_b128 v[150:153], v158 offset:1024
	ds_read_b128 v[154:157], v158 offset:2048
	ds_read_b128 v[158:161], v158 offset:3072
	s_add_u32 s34, s34, 0x40000
	s_addc_u32 s35, s35, 0
	s_mov_b32 m0, s70
	v_lshl_add_u64 v[236:237], s[34:35], 0, v[168:169]
	ds_read_b128 v[174:177], v202 offset:32768
	ds_read_b128 v[186:189], v202 offset:33792
	ds_read_b128 v[190:193], v202 offset:34816
	ds_read_b128 v[194:197], v202 offset:35840
	ds_read_b128 v[204:207], v202 offset:36864
	ds_read_b128 v[208:211], v202 offset:37888
	ds_read_b128 v[212:215], v202 offset:38912
	ds_read_b128 v[216:219], v202 offset:39936
	global_load_lds_dwordx4 v[236:237], off
	v_lshl_add_u64 v[236:237], s[34:35], 0, v[164:165]
	s_mov_b32 m0, s71
	s_nop 0
	global_load_lds_dwordx4 v[236:237], off
	s_waitcnt vmcnt(8)
	s_waitcnt lgkmcnt(0)
	s_barrier
	s_setprio 1
	s_waitcnt lgkmcnt(0)
	v_mfma_f32_16x16x32_bf16 v[126:129], v[130:133], v[174:177], v[126:129]
	v_mfma_f32_16x16x32_bf16 v[122:125], v[138:141], v[174:177], v[122:125]
	v_mfma_f32_16x16x32_bf16 v[118:121], v[130:133], v[190:193], v[118:121]
	v_mfma_f32_16x16x32_bf16 v[114:117], v[138:141], v[190:193], v[114:117]
	v_mfma_f32_16x16x32_bf16 v[94:97], v[130:133], v[204:207], v[94:97]
	v_mfma_f32_16x16x32_bf16 v[90:93], v[138:141], v[204:207], v[90:93]
	v_mfma_f32_16x16x32_bf16 v[78:81], v[130:133], v[212:215], v[78:81]
	v_mfma_f32_16x16x32_bf16 v[74:77], v[138:141], v[212:215], v[74:77]
	v_mfma_f32_16x16x32_bf16 v[126:129], v[134:137], v[186:189], v[126:129]
	v_mfma_f32_16x16x32_bf16 v[122:125], v[142:145], v[186:189], v[122:125]
	v_mfma_f32_16x16x32_bf16 v[118:121], v[134:137], v[194:197], v[118:121]
	v_mfma_f32_16x16x32_bf16 v[114:117], v[142:145], v[194:197], v[114:117]
	v_mfma_f32_16x16x32_bf16 v[94:97], v[134:137], v[208:211], v[94:97]
	v_mfma_f32_16x16x32_bf16 v[90:93], v[142:145], v[208:211], v[90:93]
	v_mfma_f32_16x16x32_bf16 v[78:81], v[134:137], v[216:219], v[78:81]
	v_mfma_f32_16x16x32_bf16 v[74:77], v[142:145], v[216:219], v[74:77]
	v_mfma_f32_16x16x32_bf16 v[110:113], v[146:149], v[174:177], v[110:113]
	v_mfma_f32_16x16x32_bf16 v[106:109], v[154:157], v[174:177], v[106:109]
	v_mfma_f32_16x16x32_bf16 v[102:105], v[146:149], v[190:193], v[102:105]
	v_mfma_f32_16x16x32_bf16 v[98:101], v[154:157], v[190:193], v[98:101]
	v_mfma_f32_16x16x32_bf16 v[86:89], v[146:149], v[204:207], v[86:89]
	v_mfma_f32_16x16x32_bf16 v[82:85], v[154:157], v[204:207], v[82:85]
	v_mfma_f32_16x16x32_bf16 v[70:73], v[146:149], v[212:215], v[70:73]
	v_mfma_f32_16x16x32_bf16 v[66:69], v[154:157], v[212:215], v[66:69]
	v_mfma_f32_16x16x32_bf16 v[110:113], v[150:153], v[186:189], v[110:113]
	v_mfma_f32_16x16x32_bf16 v[106:109], v[158:161], v[186:189], v[106:109]
	v_mfma_f32_16x16x32_bf16 v[102:105], v[150:153], v[194:197], v[102:105]
	v_mfma_f32_16x16x32_bf16 v[98:101], v[158:161], v[194:197], v[98:101]
	v_mfma_f32_16x16x32_bf16 v[86:89], v[150:153], v[208:211], v[86:89]
	v_mfma_f32_16x16x32_bf16 v[82:85], v[158:161], v[208:211], v[82:85]
	v_mfma_f32_16x16x32_bf16 v[70:73], v[150:153], v[216:219], v[70:73]
	v_mfma_f32_16x16x32_bf16 v[66:69], v[158:161], v[216:219], v[66:69]
	s_setprio 0
	s_barrier
; template <class Epi, class Sched, bool ALIGN_EPI = false, bool SP2 = false>
; __device__ __forceinline__ void gemm_phase(PG8_LAS unsigned char* lds, const Gemm g, const Sched& S, const Epi& E) {
;     ...
;             PG8_LDA(At, 1, 1); PG8_STAGE(PG8_SB(1, 0), b3, voffB); PG8_STAGE(PG8_SB(1, 1), b3 + hstepB, voffB); PG8_STAGE(PG8_SA(1, 0), a3, voffA);
;             PG8_WAIT_V(8); PG8_WAIT_L(0); PG8_BAR; PG8_MMA(1, 0, At, B0); PG8_MMA(1, 1, At, B1); PG8_BAR; PG8_SCHED;
;             } else {
;             PG8_LDB(B0, 0, 0); PG8_SCHED; PG8_LDA(At, 0, 0); PG8_STAGE(PG8_SA(1, 1), a1 + hstepA, voffA);
;             PG8_WAIT_L(8); PG8_BAR; PG8_WAIT_L(0); PG8_MMA(0, 0, At, B0); PG8_BAR; PG8_SCHED;
;             PG8_LDB(B1, 0, 1); PG8_STAGE(PG8_SB(0, 0), b2, voffB);
;             PG8_BAR; PG8_WAIT_L(0); PG8_MMA(0, 1, At, B1); PG8_BAR;
;             PG8_LDA(At, 0, 1); PG8_STAGE(PG8_SA(0, 0), a2, voffA);
;             PG8_BAR; PG8_WAIT_L(0); PG8_MMA(1, 0, At, B0); PG8_BAR; PG8_SCHED;
;             PG8_STAGE(PG8_SB(0, 1), b2 + hstepB, voffB);
;             PG8_WAIT_V(6); PG8_BAR; PG8_MMA(1, 1, At, B1); PG8_BAR;
;             PG8_LDB(B0, 1, 0); PG8_SCHED; PG8_LDA(At, 1, 0); PG8_STAGE(PG8_SA(0, 1), a2 + hstepA, voffA);
;             PG8_WAIT_L(8); PG8_BAR; PG8_WAIT_L(0); PG8_MMA(0, 0, At, B0); PG8_BAR; PG8_SCHED;
;             PG8_LDB(B1, 1, 1); PG8_STAGE(PG8_SB(1, 0), b3, voffB);
;             PG8_BAR; PG8_WAIT_L(0); PG8_MMA(0, 1, At, B1); PG8_BAR;
;             PG8_LDA(At, 1, 1); PG8_STAGE(PG8_SA(1, 0), a3, voffA);
;             PG8_BAR; PG8_WAIT_L(0); PG8_MMA(1, 0, At, B0); PG8_BAR; PG8_SCHED;
;             PG8_STAGE(PG8_SB(1, 1), b3 + hstepB, voffB);
;             PG8_WAIT_V(6); PG8_BAR; PG8_MMA(1, 1, At, B1); PG8_BAR;
;             }
;         }
;         if constexpr (ALIGN_EPI) { if (wr == 0) PG8_BAR; }
;     __device__ __forceinline__ void operator()(const f32x4 (&acc)[2][2][4][2], const Unit& u, int wr, int wc, int fr, int fq) const {
;         const int row0 = u.pm * BM + wr * 64 + fr; const int col0 = u.pn * BM + wc * 32 + 8 * fq; const int bcol0 = col0 + (u.pn >= skip_tile ? skip : 0);
;         f32x2 sv[2][4];
; #pragma unroll
;         for (int ai = 0; ai < 2; ++ai)
; #pragma unroll
;             for (int m = 0; m < 4; ++m) sv[ai][m] = *(const f32x2*)(stats + 2 * (size_t)(row0 + ai * HALF + m * 16));
;         f32x4 cv[2][2], bv[2][2];
; #pragma unroll
	s_add_i32 s4, s4, s53
	v_lshl_add_u64 v[178:179], v[178:179], 0, s[62:63]
	s_mov_b32 m0, s4
	ds_read_b128 v[174:177], v202 offset:49152
	ds_read_b128 v[186:189], v202 offset:50176
	ds_read_b128 v[190:193], v202 offset:51200
	ds_read_b128 v[194:197], v202 offset:52224
	ds_read_b128 v[204:207], v202 offset:53248
	ds_read_b128 v[208:211], v202 offset:54272
	ds_read_b128 v[212:215], v202 offset:55296
	ds_read_b128 v[216:219], v202 offset:56320
	global_load_lds_dwordx4 v[178:179], off
	s_add_i32 m0, s4, 0x2000
	s_add_u32 s24, s24, 0x40080
	v_lshl_add_u64 v[178:179], v[198:199], 0, s[62:63]
	s_addc_u32 s25, s25, 0
	s_add_i32 s4, s5, s53
	global_load_lds_dwordx4 v[178:179], off
	v_lshl_add_u64 v[178:179], s[24:25], 0, v[166:167]
	s_mov_b32 m0, s4
	s_nop 0
	global_load_lds_dwordx4 v[178:179], off
	v_lshl_add_u64 v[178:179], s[24:25], 0, v[162:163]
	s_add_i32 m0, s4, 0x2000
	s_nop 0
	global_load_lds_dwordx4 v[178:179], off
	v_lshl_add_u64 v[178:179], v[220:221], 0, s[62:63]
	s_mov_b32 m0, s74
	s_nop 0
	global_load_lds_dwordx4 v[178:179], off
	v_lshl_add_u64 v[178:179], v[234:235], 0, s[62:63]
	s_mov_b32 m0, s75
	s_nop 0
	global_load_lds_dwordx4 v[178:179], off
	s_waitcnt vmcnt(8)
	s_waitcnt lgkmcnt(0)
	s_barrier
	s_setprio 1
	s_waitcnt lgkmcnt(0)
	v_mfma_f32_16x16x32_bf16 v[62:65], v[130:133], v[174:177], v[62:65]
	v_mfma_f32_16x16x32_bf16 v[58:61], v[138:141], v[174:177], v[58:61]
	v_mfma_f32_16x16x32_bf16 v[46:49], v[130:133], v[190:193], v[46:49]
	v_mfma_f32_16x16x32_bf16 v[42:45], v[138:141], v[190:193], v[42:45]
	v_mfma_f32_16x16x32_bf16 v[30:33], v[130:133], v[204:207], v[30:33]
	v_mfma_f32_16x16x32_bf16 v[26:29], v[138:141], v[204:207], v[26:29]
	v_mfma_f32_16x16x32_bf16 v[14:17], v[130:133], v[212:215], v[14:17]
	v_mfma_f32_16x16x32_bf16 v[10:13], v[138:141], v[212:215], v[10:13]
	v_mfma_f32_16x16x32_bf16 v[62:65], v[134:137], v[186:189], v[62:65]
	v_mfma_f32_16x16x32_bf16 v[58:61], v[142:145], v[186:189], v[58:61]
	v_mfma_f32_16x16x32_bf16 v[46:49], v[134:137], v[194:197], v[46:49]
	v_mfma_f32_16x16x32_bf16 v[42:45], v[142:145], v[194:197], v[42:45]
	v_mfma_f32_16x16x32_bf16 v[30:33], v[134:137], v[208:211], v[30:33]
	v_mfma_f32_16x16x32_bf16 v[26:29], v[142:145], v[208:211], v[26:29]
	v_mfma_f32_16x16x32_bf16 v[14:17], v[134:137], v[216:219], v[14:17]
	v_mfma_f32_16x16x32_bf16 v[10:13], v[142:145], v[216:219], v[10:13]
	v_mfma_f32_16x16x32_bf16 v[54:57], v[146:149], v[174:177], v[54:57]
	v_mfma_f32_16x16x32_bf16 v[50:53], v[154:157], v[174:177], v[50:53]
	v_mfma_f32_16x16x32_bf16 v[38:41], v[146:149], v[190:193], v[38:41]
	v_mfma_f32_16x16x32_bf16 v[34:37], v[154:157], v[190:193], v[34:37]
	v_mfma_f32_16x16x32_bf16 v[22:25], v[146:149], v[204:207], v[22:25]
	v_mfma_f32_16x16x32_bf16 v[18:21], v[154:157], v[204:207], v[18:21]
	v_mfma_f32_16x16x32_bf16 v[6:9], v[146:149], v[212:215], v[6:9]
	v_mfma_f32_16x16x32_bf16 v[2:5], v[154:157], v[212:215], v[2:5]
	v_mfma_f32_16x16x32_bf16 v[54:57], v[150:153], v[186:189], v[54:57]
	v_mfma_f32_16x16x32_bf16 v[50:53], v[158:161], v[186:189], v[50:53]
	v_mfma_f32_16x16x32_bf16 v[38:41], v[150:153], v[194:197], v[38:41]
	v_mfma_f32_16x16x32_bf16 v[34:37], v[158:161], v[194:197], v[34:37]
	v_mfma_f32_16x16x32_bf16 v[22:25], v[150:153], v[208:211], v[22:25]
	v_mfma_f32_16x16x32_bf16 v[18:21], v[158:161], v[208:211], v[18:21]
	v_mfma_f32_16x16x32_bf16 v[6:9], v[150:153], v[216:219], v[6:9]
	v_mfma_f32_16x16x32_bf16 v[2:5], v[158:161], v[216:219], v[2:5]
	s_setprio 0
	s_barrier
	s_add_i32 s76, s76, 2
	s_add_u32 s50, s50, 0x100
	s_addc_u32 s51, s51, 0
	s_add_u32 s90, s90, 0x100
	s_addc_u32 s91, s91, 0
	s_cmp_gt_u32 s76, 13
	s_cbranch_scc0 .LBB0_815
	s_and_b64 vcc, exec, s[30:31]
	s_cbranch_vccz .LBB0_818
	s_barrier
.LBB0_818:
	v_lshl_add_u32 v178, s82, 8, v1
	v_ashrrev_i32_e32 v179, 31, v178
	v_lshl_or_b32 v188, s81, 8, v201
	v_lshl_add_u64 v[130:131], v[178:179], 3, s[46:47]
	v_ashrrev_i32_e32 v189, 31, v188
	v_or_b32_e32 v192, 16, v178
	global_load_dwordx2 v[204:205], v[130:131], off
	v_lshlrev_b64 v[138:139], 2, v[188:189]
	v_ashrrev_i32_e32 v193, 31, v192
	v_lshl_add_u64 v[134:135], s[18:19], 0, v[138:139]
	v_lshl_add_u64 v[140:141], v[192:193], 3, s[46:47]
	global_load_dwordx4 v[154:157], v[134:135], off
	global_load_dwordx4 v[146:149], v[134:135], off offset:16
	global_load_dwordx4 v[130:133], v[134:135], off offset:528
	s_nop 0
	global_load_dwordx4 v[134:137], v[134:135], off offset:512
	v_lshl_add_u64 v[138:139], s[22:23], 0, v[138:139]
	global_load_dwordx2 v[206:207], v[140:141], off
	global_load_dwordx4 v[158:161], v[138:139], off
	global_load_dwordx4 v[150:153], v[138:139], off offset:16
	global_load_dwordx4 v[142:145], v[138:139], off offset:512
	s_nop 0
	global_load_dwordx4 v[138:141], v[138:139], off offset:528
	v_or_b32_e32 v208, 32, v178
	v_mov_b64_e32 v[174:175], s[66:67]
	v_ashrrev_i32_e32 v209, 31, v208
	v_or_b32_e32 v198, 48, v178
	v_add_u32_e32 v194, 0x80, v178
	v_add_u32_e32 v190, 0x90, v178
	v_add_u32_e32 v186, 0xa0, v178
	v_add_u32_e32 v176, 0xb0, v178
	v_mad_i64_i32 v[196:197], s[24:25], v178, s69, v[174:175]
	v_lshl_add_u64 v[178:179], v[208:209], 3, s[46:47]
	global_load_dwordx2 v[210:211], v[178:179], off
	v_ashrrev_i32_e32 v199, 31, v198
	v_ashrrev_i32_e32 v195, 31, v194
	v_ashrrev_i32_e32 v191, 31, v190
	v_ashrrev_i32_e32 v187, 31, v186
	v_ashrrev_i32_e32 v177, 31, v176
	v_lshlrev_b64 v[178:179], 1, v[188:189]
	v_mad_i64_i32 v[188:189], s[24:25], v192, s69, v[174:175]
	v_lshl_add_u64 v[192:193], v[198:199], 3, s[46:47]
	v_lshl_add_u64 v[212:213], v[194:195], 3, s[46:47]
	v_lshl_add_u64 v[214:215], v[190:191], 3, s[46:47]
	v_lshl_add_u64 v[216:217], v[186:187], 3, s[46:47]
	v_lshl_add_u64 v[218:219], v[176:177], 3, s[46:47]
	v_lshl_add_u64 v[220:221], v[196:197], 0, v[178:179]
	v_lshl_add_u64 v[234:235], v[188:189], 0, v[178:179]
	global_load_dwordx2 v[236:237], v[192:193], off
	s_nop 0
	global_load_dwordx2 v[212:213], v[212:213], off
	s_nop 0
	global_load_dwordx2 v[196:197], v[214:215], off
	global_load_dwordx2 v[192:193], v[216:217], off
	global_load_dwordx2 v[188:189], v[218:219], off
	v_readlane_b32 s50, v255, 58
	s_andn2_b64 vcc, exec, s[40:41]
	v_readlane_b32 s51, v255, 59
	s_waitcnt vmcnt(0)
; __device__ __forceinline__ unsigned cvt_pk_bf16(float lo, float hi) { unsigned r; asm volatile("v_cvt_pk_bf16_f32 %0, %1, %2" : "=v"(r) : "v"(lo), "v"(hi)); return r; }
; __device__ __forceinline__ void stats_mr(const f32x2 s, float& mu, float& r) { mu = s.x * (1.0f / 1024.0f); const float var = s.y * (1.0f / 1024.0f) - mu * mu; r = __builtin_amdgcn_rsqf(var + 1e-5f); }
; template <class Epi, class Sched, bool ALIGN_EPI = false, bool SP2 = false>
; __device__ __forceinline__ void gemm_phase(PG8_LAS unsigned char* lds, const Gemm g, const Sched& S, const Epi& E) {
;     ...
;         for (int a = 0; a < 2; ++a)
; #pragma unroll
;             for (int b = 0; b < 2; ++b)
; #pragma unroll
;                 for (int m = 0; m < 4; ++m)
; #pragma unroll
;                     for (int n = 0; n < 2; ++n) acc[a][b][m][n] = (f32x4){0.f, 0.f, 0.f, 0.f};
;     __device__ __forceinline__ void operator()(const f32x4 (&acc)[2][2][4][2], const Unit& u, int wr, int wc, int fr, int fq) const {
;     ...
;         for (int ai = 0; ai < 2; ++ai)
; #pragma unroll
;             for (int m = 0; m < 4; ++m) { const int row = row0 + ai * HALF + m * 16; bf16_t* rowp = O + (size_t)row * ldc + col0;
;                 float mu, r; stats_mr(sv[ai][m], mu, r);
; #pragma unroll
;                 for (int bj = 0; bj < 2; ++bj) { const f32x4 v0 = (acc[ai][bj][m][0] - cv[bj][0] * mu) * r + bv[bj][0], v1 = (acc[ai][bj][m][1] - cv[bj][1] * mu) * r + bv[bj][1];
;                     u32x4 w; w.x = cvt_pk_bf16(v0[0], v0[1]); w.y = cvt_pk_bf16(v0[2], v0[3]); w.z = cvt_pk_bf16(v1[0], v1[1]); w.w = cvt_pk_bf16(v1[2], v1[3]);
;                     *(u32x4*)(rowp + bj * HALF) = w; } }
	v_pk_mul_f32 v[204:205], v[204:205], s[54:55] op_sel_hi:[1,0]
	s_nop 0
	v_fma_f32 v177, -v204, v204, v205
	v_pk_fma_f32 v[126:127], v[204:205], v[154:155], v[126:127] op_sel_hi:[0,1,1] neg_lo:[1,0,0] neg_hi:[1,0,0]
	v_pk_fma_f32 v[128:129], v[204:205], v[156:157], v[128:129] op_sel_hi:[0,1,1] neg_lo:[1,0,0] neg_hi:[1,0,0]
	v_pk_fma_f32 v[122:123], v[204:205], v[146:147], v[122:123] op_sel_hi:[0,1,1] neg_lo:[1,0,0] neg_hi:[1,0,0]
	v_pk_fma_f32 v[124:125], v[204:205], v[148:149], v[124:125] op_sel_hi:[0,1,1] neg_lo:[1,0,0] neg_hi:[1,0,0]
	v_pk_fma_f32 v[110:111], v[204:205], v[134:135], v[110:111] op_sel_hi:[0,1,1] neg_lo:[1,0,0] neg_hi:[1,0,0]
	v_pk_fma_f32 v[112:113], v[204:205], v[136:137], v[112:113] op_sel_hi:[0,1,1] neg_lo:[1,0,0] neg_hi:[1,0,0]
	v_pk_fma_f32 v[106:107], v[204:205], v[130:131], v[106:107] op_sel_hi:[0,1,1] neg_lo:[1,0,0] neg_hi:[1,0,0]
	v_pk_fma_f32 v[108:109], v[204:205], v[132:133], v[108:109] op_sel_hi:[0,1,1] neg_lo:[1,0,0] neg_hi:[1,0,0]
	v_pk_mul_f32 v[204:205], v[206:207], s[54:55] op_sel_hi:[1,0]
	v_add_f32_e32 v177, 0x3727c5ac, v177
	v_fma_f32 v187, -v204, v204, v205
	v_rsq_f32_e32 v206, v177
	v_add_f32_e32 v177, 0x3727c5ac, v187
	v_rsq_f32_e32 v214, v177
	v_pk_fma_f32 v[118:119], v[204:205], v[154:155], v[118:119] op_sel_hi:[0,1,1] neg_lo:[1,0,0] neg_hi:[1,0,0]
	v_pk_fma_f32 v[128:129], v[206:207], v[128:129], v[160:161] op_sel_hi:[0,1,1]
	v_pk_fma_f32 v[126:127], v[206:207], v[126:127], v[158:159] op_sel_hi:[0,1,1]
	v_pk_fma_f32 v[124:125], v[206:207], v[124:125], v[152:153] op_sel_hi:[0,1,1]
	v_pk_fma_f32 v[122:123], v[206:207], v[122:123], v[150:151] op_sel_hi:[0,1,1]
	v_pk_fma_f32 v[112:113], v[206:207], v[112:113], v[144:145] op_sel_hi:[0,1,1]
	v_pk_fma_f32 v[110:111], v[206:207], v[110:111], v[142:143] op_sel_hi:[0,1,1]
	v_pk_fma_f32 v[216:217], v[206:207], v[108:109], v[140:141] op_sel_hi:[0,1,1]
	v_pk_fma_f32 v[206:207], v[206:207], v[106:107], v[138:139] op_sel_hi:[0,1,1]
	v_cvt_pk_bf16_f32 v106, v126, v127
	v_mov_b32_e32 v126, 0
	v_mov_b32_e32 v127, 0
	v_cvt_pk_bf16_f32 v107, v128, v129
	v_mov_b32_e32 v128, 0
	v_mov_b32_e32 v129, 0
	v_cvt_pk_bf16_f32 v108, v122, v123
	v_mov_b32_e32 v122, 0
	v_mov_b32_e32 v123, 0
	v_cvt_pk_bf16_f32 v109, v124, v125
	v_mov_b32_e32 v124, 0
	v_mov_b32_e32 v125, 0
	v_pk_fma_f32 v[120:121], v[204:205], v[156:157], v[120:121] op_sel_hi:[0,1,1] neg_lo:[1,0,0] neg_hi:[1,0,0]
	v_pk_fma_f32 v[114:115], v[204:205], v[146:147], v[114:115] op_sel_hi:[0,1,1] neg_lo:[1,0,0] neg_hi:[1,0,0]
	global_store_dwordx4 v[220:221], v[106:109], off
	v_pk_fma_f32 v[116:117], v[204:205], v[148:149], v[116:117] op_sel_hi:[0,1,1] neg_lo:[1,0,0] neg_hi:[1,0,0]
	v_pk_fma_f32 v[120:121], v[214:215], v[120:121], v[160:161] op_sel_hi:[0,1,1]
	v_cvt_pk_bf16_f32 v106, v110, v111
	v_mov_b32_e32 v110, 0
	v_mov_b32_e32 v111, 0
	v_cvt_pk_bf16_f32 v107, v112, v113
	v_mov_b32_e32 v112, 0
	v_mov_b32_e32 v113, 0
	v_cvt_pk_bf16_f32 v108, v206, v207
	v_cvt_pk_bf16_f32 v109, v216, v217
	v_pk_fma_f32 v[118:119], v[214:215], v[118:119], v[158:159] op_sel_hi:[0,1,1]
	global_store_dwordx4 v[220:221], v[106:109], off offset:256
	v_pk_fma_f32 v[98:99], v[204:205], v[130:131], v[98:99] op_sel_hi:[0,1,1] neg_lo:[1,0,0] neg_hi:[1,0,0]
	v_pk_fma_f32 v[100:101], v[204:205], v[132:133], v[100:101] op_sel_hi:[0,1,1] neg_lo:[1,0,0] neg_hi:[1,0,0]
	v_pk_fma_f32 v[108:109], v[214:215], v[114:115], v[150:151] op_sel_hi:[0,1,1]
	v_mov_b32_e32 v114, 0
	v_mov_b32_e32 v115, 0
	v_cvt_pk_bf16_f32 v106, v118, v119
	v_mov_b32_e32 v118, 0
	v_mov_b32_e32 v119, 0
	v_cvt_pk_bf16_f32 v107, v120, v121
	v_mov_b32_e32 v120, 0
	v_mov_b32_e32 v121, 0
	v_pk_fma_f32 v[116:117], v[214:215], v[116:117], v[152:153] op_sel_hi:[0,1,1]
	v_cvt_pk_bf16_f32 v108, v108, v109
	v_cvt_pk_bf16_f32 v109, v116, v117
	v_mov_b32_e32 v116, 0
	v_mov_b32_e32 v117, 0
	global_store_dwordx4 v[234:235], v[106:109], off
	s_nop 1
	v_mov_b32_e32 v108, 0
	v_mov_b32_e32 v109, 0
	v_pk_fma_f32 v[102:103], v[204:205], v[134:135], v[102:103] op_sel_hi:[0,1,1] neg_lo:[1,0,0] neg_hi:[1,0,0]
	v_pk_fma_f32 v[104:105], v[204:205], v[136:137], v[104:105] op_sel_hi:[0,1,1] neg_lo:[1,0,0] neg_hi:[1,0,0]
	v_pk_fma_f32 v[106:107], v[214:215], v[100:101], v[140:141] op_sel_hi:[0,1,1]
	v_pk_fma_f32 v[100:101], v[214:215], v[98:99], v[138:139] op_sel_hi:[0,1,1]
	v_pk_fma_f32 v[104:105], v[214:215], v[104:105], v[144:145] op_sel_hi:[0,1,1]
	v_pk_fma_f32 v[102:103], v[214:215], v[102:103], v[142:143] op_sel_hi:[0,1,1]
	v_cvt_pk_bf16_f32 v98, v102, v103
	v_cvt_pk_bf16_f32 v99, v104, v105
	v_cvt_pk_bf16_f32 v100, v100, v101
	v_cvt_pk_bf16_f32 v101, v106, v107
	v_mov_b32_e32 v106, 0
	v_mov_b32_e32 v107, 0
	global_store_dwordx4 v[234:235], v[98:101], off offset:256
	s_nop 1
	v_pk_mul_f32 v[100:101], v[210:211], s[54:55] op_sel_hi:[1,0]
	v_mad_i64_i32 v[98:99], s[24:25], v208, s69, v[174:175]
	v_fma_f32 v102, -v100, v100, v101
	v_add_f32_e32 v102, 0x3727c5ac, v102
	v_rsq_f32_e32 v102, v102
	v_pk_fma_f32 v[94:95], v[100:101], v[154:155], v[94:95] op_sel_hi:[0,1,1] neg_lo:[1,0,0] neg_hi:[1,0,0]
	v_pk_fma_f32 v[96:97], v[100:101], v[156:157], v[96:97] op_sel_hi:[0,1,1] neg_lo:[1,0,0] neg_hi:[1,0,0]
	v_pk_fma_f32 v[90:91], v[100:101], v[146:147], v[90:91] op_sel_hi:[0,1,1] neg_lo:[1,0,0] neg_hi:[1,0,0]
	v_pk_fma_f32 v[92:93], v[100:101], v[148:149], v[92:93] op_sel_hi:[0,1,1] neg_lo:[1,0,0] neg_hi:[1,0,0]
	v_lshl_add_u64 v[98:99], v[98:99], 0, v[178:179]
	v_pk_fma_f32 v[96:97], v[102:103], v[96:97], v[160:161] op_sel_hi:[0,1,1]
	v_pk_fma_f32 v[94:95], v[102:103], v[94:95], v[158:159] op_sel_hi:[0,1,1]
	v_pk_fma_f32 v[104:105], v[102:103], v[92:93], v[152:153] op_sel_hi:[0,1,1]
; __device__ __forceinline__ unsigned cvt_pk_bf16(float lo, float hi) { unsigned r; asm volatile("v_cvt_pk_bf16_f32 %0, %1, %2" : "=v"(r) : "v"(lo), "v"(hi)); return r; }
; __device__ __forceinline__ void stats_mr(const f32x2 s, float& mu, float& r) { mu = s.x * (1.0f / 1024.0f); const float var = s.y * (1.0f / 1024.0f) - mu * mu; r = __builtin_amdgcn_rsqf(var + 1e-5f); }
; template <class Epi, class Sched, bool ALIGN_EPI = false, bool SP2 = false>
; __device__ __forceinline__ void gemm_phase(PG8_LAS unsigned char* lds, const Gemm g, const Sched& S, const Epi& E) {
;     ...
;         for (int a = 0; a < 2; ++a)
; #pragma unroll
;             for (int b = 0; b < 2; ++b)
; #pragma unroll
;                 for (int m = 0; m < 4; ++m)
; #pragma unroll
;                     for (int n = 0; n < 2; ++n) acc[a][b][m][n] = (f32x4){0.f, 0.f, 0.f, 0.f};
;     __device__ __forceinline__ void operator()(const f32x4 (&acc)[2][2][4][2], const Unit& u, int wr, int wc, int fr, int fq) const {
;     ...
;         for (int ai = 0; ai < 2; ++ai)
; #pragma unroll
;             for (int m = 0; m < 4; ++m) { const int row = row0 + ai * HALF + m * 16; bf16_t* rowp = O + (size_t)row * ldc + col0;
;                 float mu, r; stats_mr(sv[ai][m], mu, r);
; #pragma unroll
;                 for (int bj = 0; bj < 2; ++bj) { const f32x4 v0 = (acc[ai][bj][m][0] - cv[bj][0] * mu) * r + bv[bj][0], v1 = (acc[ai][bj][m][1] - cv[bj][1] * mu) * r + bv[bj][1];
;                     u32x4 w; w.x = cvt_pk_bf16(v0[0], v0[1]); w.y = cvt_pk_bf16(v0[2], v0[3]); w.z = cvt_pk_bf16(v1[0], v1[1]); w.w = cvt_pk_bf16(v1[2], v1[3]);
;                     *(u32x4*)(rowp + bj * HALF) = w; } }
	v_pk_fma_f32 v[92:93], v[102:103], v[90:91], v[150:151] op_sel_hi:[0,1,1]
	v_cvt_pk_bf16_f32 v90, v94, v95
	v_mov_b32_e32 v94, 0
	v_mov_b32_e32 v95, 0
	v_cvt_pk_bf16_f32 v91, v96, v97
	v_mov_b32_e32 v96, 0
	v_mov_b32_e32 v97, 0
	v_pk_fma_f32 v[82:83], v[100:101], v[130:131], v[82:83] op_sel_hi:[0,1,1] neg_lo:[1,0,0] neg_hi:[1,0,0]
	v_pk_fma_f32 v[84:85], v[100:101], v[132:133], v[84:85] op_sel_hi:[0,1,1] neg_lo:[1,0,0] neg_hi:[1,0,0]
	v_cvt_pk_bf16_f32 v92, v92, v93
	v_cvt_pk_bf16_f32 v93, v104, v105
	v_mov_b32_e32 v104, 0
	v_mov_b32_e32 v105, 0
	global_store_dwordx4 v[98:99], v[90:93], off
	s_nop 1
	v_mov_b32_e32 v92, 0
	v_mov_b32_e32 v93, 0
	v_pk_fma_f32 v[86:87], v[100:101], v[134:135], v[86:87] op_sel_hi:[0,1,1] neg_lo:[1,0,0] neg_hi:[1,0,0]
	v_pk_fma_f32 v[88:89], v[100:101], v[136:137], v[88:89] op_sel_hi:[0,1,1] neg_lo:[1,0,0] neg_hi:[1,0,0]
	v_mov_b32_e32 v100, 0
	v_mov_b32_e32 v101, 0
	v_pk_fma_f32 v[90:91], v[102:103], v[84:85], v[140:141] op_sel_hi:[0,1,1]
	v_pk_fma_f32 v[84:85], v[102:103], v[82:83], v[138:139] op_sel_hi:[0,1,1]
	v_pk_fma_f32 v[88:89], v[102:103], v[88:89], v[144:145] op_sel_hi:[0,1,1]
	v_pk_fma_f32 v[86:87], v[102:103], v[86:87], v[142:143] op_sel_hi:[0,1,1]
	v_mov_b32_e32 v102, 0
	v_mov_b32_e32 v103, 0
	v_cvt_pk_bf16_f32 v82, v86, v87
	v_cvt_pk_bf16_f32 v83, v88, v89
	v_cvt_pk_bf16_f32 v84, v84, v85
	v_cvt_pk_bf16_f32 v85, v90, v91
	v_mov_b32_e32 v90, 0
	v_mov_b32_e32 v91, 0
	global_store_dwordx4 v[98:99], v[82:85], off offset:256
	s_nop 1
	v_mov_b32_e32 v98, 0
	v_mov_b32_e32 v99, 0
	s_nop 1
	v_pk_mul_f32 v[84:85], v[236:237], s[54:55] op_sel_hi:[1,0]
	v_mad_i64_i32 v[82:83], s[24:25], v198, s69, v[174:175]
	v_fma_f32 v86, -v84, v84, v85
	v_add_f32_e32 v86, 0x3727c5ac, v86
	v_rsq_f32_e32 v86, v86
	v_pk_fma_f32 v[78:79], v[84:85], v[154:155], v[78:79] op_sel_hi:[0,1,1] neg_lo:[1,0,0] neg_hi:[1,0,0]
	v_pk_fma_f32 v[80:81], v[84:85], v[156:157], v[80:81] op_sel_hi:[0,1,1] neg_lo:[1,0,0] neg_hi:[1,0,0]
	v_pk_fma_f32 v[74:75], v[84:85], v[146:147], v[74:75] op_sel_hi:[0,1,1] neg_lo:[1,0,0] neg_hi:[1,0,0]
	v_pk_fma_f32 v[76:77], v[84:85], v[148:149], v[76:77] op_sel_hi:[0,1,1] neg_lo:[1,0,0] neg_hi:[1,0,0]
	v_lshl_add_u64 v[82:83], v[82:83], 0, v[178:179]
	v_pk_fma_f32 v[80:81], v[80:81], v[86:87], v[160:161] op_sel_hi:[1,0,1]
	v_pk_fma_f32 v[78:79], v[78:79], v[86:87], v[158:159] op_sel_hi:[1,0,1]
	v_pk_fma_f32 v[88:89], v[86:87], v[76:77], v[152:153] op_sel_hi:[0,1,1]
	v_pk_fma_f32 v[76:77], v[86:87], v[74:75], v[150:151] op_sel_hi:[0,1,1]
	v_cvt_pk_bf16_f32 v74, v78, v79
	v_mov_b32_e32 v78, 0
	v_mov_b32_e32 v79, 0
	v_cvt_pk_bf16_f32 v75, v80, v81
	v_mov_b32_e32 v80, 0
	v_mov_b32_e32 v81, 0
	v_pk_fma_f32 v[66:67], v[84:85], v[130:131], v[66:67] op_sel_hi:[0,1,1] neg_lo:[1,0,0] neg_hi:[1,0,0]
	v_pk_fma_f32 v[68:69], v[84:85], v[132:133], v[68:69] op_sel_hi:[0,1,1] neg_lo:[1,0,0] neg_hi:[1,0,0]
	v_cvt_pk_bf16_f32 v76, v76, v77
	v_cvt_pk_bf16_f32 v77, v88, v89
	v_mov_b32_e32 v88, 0
	v_mov_b32_e32 v89, 0
	global_store_dwordx4 v[82:83], v[74:77], off
	s_nop 1
	v_mov_b32_e32 v76, 0
	v_mov_b32_e32 v77, 0
	v_pk_fma_f32 v[70:71], v[84:85], v[134:135], v[70:71] op_sel_hi:[0,1,1] neg_lo:[1,0,0] neg_hi:[1,0,0]
	v_pk_fma_f32 v[72:73], v[84:85], v[136:137], v[72:73] op_sel_hi:[0,1,1] neg_lo:[1,0,0] neg_hi:[1,0,0]
	v_mov_b32_e32 v84, 0
	v_mov_b32_e32 v85, 0
	v_pk_fma_f32 v[74:75], v[86:87], v[68:69], v[140:141] op_sel_hi:[0,1,1]
	v_pk_fma_f32 v[68:69], v[86:87], v[66:67], v[138:139] op_sel_hi:[0,1,1]
	v_pk_fma_f32 v[72:73], v[86:87], v[72:73], v[144:145] op_sel_hi:[0,1,1]
	v_pk_fma_f32 v[70:71], v[86:87], v[70:71], v[142:143] op_sel_hi:[0,1,1]
	v_mov_b32_e32 v86, 0
	v_mov_b32_e32 v87, 0
	v_cvt_pk_bf16_f32 v66, v70, v71
	v_cvt_pk_bf16_f32 v67, v72, v73
	v_cvt_pk_bf16_f32 v68, v68, v69
	v_cvt_pk_bf16_f32 v69, v74, v75
	v_mov_b32_e32 v74, 0
	v_mov_b32_e32 v75, 0
	global_store_dwordx4 v[82:83], v[66:69], off offset:256
	s_nop 1
	v_mov_b32_e32 v82, 0
	v_mov_b32_e32 v83, 0
	s_nop 1
	v_pk_mul_f32 v[68:69], v[212:213], s[54:55] op_sel_hi:[1,0]
	v_mad_i64_i32 v[66:67], s[24:25], v194, s69, v[174:175]
	v_fma_f32 v70, -v68, v68, v69
	v_add_f32_e32 v70, 0x3727c5ac, v70
	v_rsq_f32_e32 v70, v70
	v_pk_fma_f32 v[62:63], v[68:69], v[154:155], v[62:63] op_sel_hi:[0,1,1] neg_lo:[1,0,0] neg_hi:[1,0,0]
	v_pk_fma_f32 v[64:65], v[68:69], v[156:157], v[64:65] op_sel_hi:[0,1,1] neg_lo:[1,0,0] neg_hi:[1,0,0]
	v_pk_fma_f32 v[58:59], v[68:69], v[146:147], v[58:59] op_sel_hi:[0,1,1] neg_lo:[1,0,0] neg_hi:[1,0,0]
	v_pk_fma_f32 v[60:61], v[68:69], v[148:149], v[60:61] op_sel_hi:[0,1,1] neg_lo:[1,0,0] neg_hi:[1,0,0]
	v_lshl_add_u64 v[66:67], v[66:67], 0, v[178:179]
	v_pk_fma_f32 v[64:65], v[64:65], v[70:71], v[160:161] op_sel_hi:[1,0,1]
	v_pk_fma_f32 v[62:63], v[62:63], v[70:71], v[158:159] op_sel_hi:[1,0,1]
	v_pk_fma_f32 v[72:73], v[70:71], v[60:61], v[152:153] op_sel_hi:[0,1,1]
	v_pk_fma_f32 v[60:61], v[70:71], v[58:59], v[150:151] op_sel_hi:[0,1,1]
	v_cvt_pk_bf16_f32 v58, v62, v63
	v_mov_b32_e32 v62, 0
	v_mov_b32_e32 v63, 0
	v_cvt_pk_bf16_f32 v59, v64, v65
	v_mov_b32_e32 v64, 0
	v_mov_b32_e32 v65, 0
	v_pk_fma_f32 v[50:51], v[68:69], v[130:131], v[50:51] op_sel_hi:[0,1,1] neg_lo:[1,0,0] neg_hi:[1,0,0]
	v_pk_fma_f32 v[52:53], v[68:69], v[132:133], v[52:53] op_sel_hi:[0,1,1] neg_lo:[1,0,0] neg_hi:[1,0,0]
	v_cvt_pk_bf16_f32 v60, v60, v61
	v_cvt_pk_bf16_f32 v61, v72, v73
	v_mov_b32_e32 v72, 0
	v_mov_b32_e32 v73, 0
	global_store_dwordx4 v[66:67], v[58:61], off
	s_nop 1
	v_mov_b32_e32 v60, 0
	v_mov_b32_e32 v61, 0
	v_pk_fma_f32 v[54:55], v[68:69], v[134:135], v[54:55] op_sel_hi:[0,1,1] neg_lo:[1,0,0] neg_hi:[1,0,0]
; __device__ __forceinline__ unsigned cvt_pk_bf16(float lo, float hi) { unsigned r; asm volatile("v_cvt_pk_bf16_f32 %0, %1, %2" : "=v"(r) : "v"(lo), "v"(hi)); return r; }
; __device__ __forceinline__ void stats_mr(const f32x2 s, float& mu, float& r) { mu = s.x * (1.0f / 1024.0f); const float var = s.y * (1.0f / 1024.0f) - mu * mu; r = __builtin_amdgcn_rsqf(var + 1e-5f); }
; template <class Epi, class Sched, bool ALIGN_EPI = false, bool SP2 = false>
; __device__ __forceinline__ void gemm_phase(PG8_LAS unsigned char* lds, const Gemm g, const Sched& S, const Epi& E) {
;     ...
;         for (int a = 0; a < 2; ++a)
; #pragma unroll
;             for (int b = 0; b < 2; ++b)
; #pragma unroll
;                 for (int m = 0; m < 4; ++m)
; #pragma unroll
;                     for (int n = 0; n < 2; ++n) acc[a][b][m][n] = (f32x4){0.f, 0.f, 0.f, 0.f};
;     __device__ __forceinline__ void operator()(const f32x4 (&acc)[2][2][4][2], const Unit& u, int wr, int wc, int fr, int fq) const {
;     ...
;         for (int ai = 0; ai < 2; ++ai)
; #pragma unroll
;             for (int m = 0; m < 4; ++m) { const int row = row0 + ai * HALF + m * 16; bf16_t* rowp = O + (size_t)row * ldc + col0;
;                 float mu, r; stats_mr(sv[ai][m], mu, r);
; #pragma unroll
;                 for (int bj = 0; bj < 2; ++bj) { const f32x4 v0 = (acc[ai][bj][m][0] - cv[bj][0] * mu) * r + bv[bj][0], v1 = (acc[ai][bj][m][1] - cv[bj][1] * mu) * r + bv[bj][1];
;                     u32x4 w; w.x = cvt_pk_bf16(v0[0], v0[1]); w.y = cvt_pk_bf16(v0[2], v0[3]); w.z = cvt_pk_bf16(v1[0], v1[1]); w.w = cvt_pk_bf16(v1[2], v1[3]);
;                     *(u32x4*)(rowp + bj * HALF) = w; } }
	v_pk_fma_f32 v[56:57], v[68:69], v[136:137], v[56:57] op_sel_hi:[0,1,1] neg_lo:[1,0,0] neg_hi:[1,0,0]
	v_mov_b32_e32 v68, 0
	v_mov_b32_e32 v69, 0
	v_pk_fma_f32 v[58:59], v[70:71], v[52:53], v[140:141] op_sel_hi:[0,1,1]
	v_pk_fma_f32 v[52:53], v[70:71], v[50:51], v[138:139] op_sel_hi:[0,1,1]
	v_pk_fma_f32 v[56:57], v[70:71], v[56:57], v[144:145] op_sel_hi:[0,1,1]
	v_pk_fma_f32 v[54:55], v[70:71], v[54:55], v[142:143] op_sel_hi:[0,1,1]
	v_mov_b32_e32 v70, 0
	v_mov_b32_e32 v71, 0
	v_cvt_pk_bf16_f32 v50, v54, v55
	v_cvt_pk_bf16_f32 v51, v56, v57
	v_cvt_pk_bf16_f32 v52, v52, v53
	v_cvt_pk_bf16_f32 v53, v58, v59
	global_store_dwordx4 v[66:67], v[50:53], off offset:256
	s_nop 1
	v_mov_b32_e32 v66, 0
	v_mov_b32_e32 v67, 0
	v_xor_b32_e32 v57, 0x80000000, v157
	v_xor_b32_e32 v56, 0x80000000, v156
	v_pk_mul_f32 v[52:53], v[196:197], s[54:55] op_sel_hi:[1,0]
	v_mad_i64_i32 v[50:51], s[24:25], v190, s69, v[174:175]
	v_fma_f32 v54, -v52, v52, v53
	v_add_f32_e32 v54, 0x3727c5ac, v54
	v_rsq_f32_e32 v54, v54
	v_pk_fma_f32 v[46:47], v[154:155], v[52:53], v[46:47] op_sel_hi:[1,0,1] neg_lo:[1,0,0] neg_hi:[1,0,0]
	v_pk_fma_f32 v[48:49], v[56:57], v[52:53], v[48:49] op_sel_hi:[1,0,1]
	v_pk_fma_f32 v[42:43], v[52:53], v[146:147], v[42:43] op_sel_hi:[0,1,1] neg_lo:[1,0,0] neg_hi:[1,0,0]
	v_pk_fma_f32 v[44:45], v[52:53], v[148:149], v[44:45] op_sel_hi:[0,1,1] neg_lo:[1,0,0] neg_hi:[1,0,0]
	v_lshl_add_u64 v[50:51], v[50:51], 0, v[178:179]
	v_pk_fma_f32 v[48:49], v[48:49], v[54:55], v[160:161] op_sel_hi:[1,0,1]
	v_pk_fma_f32 v[46:47], v[46:47], v[54:55], v[158:159] op_sel_hi:[1,0,1]
	v_pk_fma_f32 v[58:59], v[44:45], v[54:55], v[152:153] op_sel_hi:[1,0,1]
	v_pk_fma_f32 v[44:45], v[42:43], v[54:55], v[150:151] op_sel_hi:[1,0,1]
	v_cvt_pk_bf16_f32 v42, v46, v47
	v_mov_b32_e32 v46, 0
	v_mov_b32_e32 v47, 0
	v_cvt_pk_bf16_f32 v43, v48, v49
	v_mov_b32_e32 v48, 0
	v_mov_b32_e32 v49, 0
	v_pk_fma_f32 v[34:35], v[52:53], v[130:131], v[34:35] op_sel_hi:[0,1,1] neg_lo:[1,0,0] neg_hi:[1,0,0]
	v_pk_fma_f32 v[36:37], v[52:53], v[132:133], v[36:37] op_sel_hi:[0,1,1] neg_lo:[1,0,0] neg_hi:[1,0,0]
	v_cvt_pk_bf16_f32 v44, v44, v45
	v_cvt_pk_bf16_f32 v45, v58, v59
	v_mov_b32_e32 v58, 0
	v_mov_b32_e32 v59, 0
	global_store_dwordx4 v[50:51], v[42:45], off
	s_nop 1
	v_mov_b32_e32 v44, 0
	v_mov_b32_e32 v45, 0
	v_pk_fma_f32 v[38:39], v[52:53], v[134:135], v[38:39] op_sel_hi:[0,1,1] neg_lo:[1,0,0] neg_hi:[1,0,0]
	v_pk_fma_f32 v[40:41], v[52:53], v[136:137], v[40:41] op_sel_hi:[0,1,1] neg_lo:[1,0,0] neg_hi:[1,0,0]
	v_mov_b32_e32 v52, 0
	v_mov_b32_e32 v53, 0
	v_pk_fma_f32 v[42:43], v[54:55], v[36:37], v[140:141] op_sel_hi:[0,1,1]
	v_pk_fma_f32 v[36:37], v[54:55], v[34:35], v[138:139] op_sel_hi:[0,1,1]
	v_pk_fma_f32 v[40:41], v[54:55], v[40:41], v[144:145] op_sel_hi:[0,1,1]
	v_pk_fma_f32 v[38:39], v[54:55], v[38:39], v[142:143] op_sel_hi:[0,1,1]
	v_mov_b32_e32 v54, 0
	v_mov_b32_e32 v55, 0
	v_cvt_pk_bf16_f32 v34, v38, v39
	v_cvt_pk_bf16_f32 v35, v40, v41
	v_cvt_pk_bf16_f32 v36, v36, v37
	v_cvt_pk_bf16_f32 v37, v42, v43
	v_mov_b32_e32 v42, 0
	v_mov_b32_e32 v43, 0
	global_store_dwordx4 v[50:51], v[34:37], off offset:256
	s_nop 1
	v_mov_b32_e32 v50, 0
	v_mov_b32_e32 v51, 0
	s_nop 1
	v_pk_mul_f32 v[36:37], v[192:193], s[54:55] op_sel_hi:[1,0]
	v_mad_i64_i32 v[34:35], s[24:25], v186, s69, v[174:175]
	v_fma_f32 v38, -v36, v36, v37
	v_add_f32_e32 v38, 0x3727c5ac, v38
	v_rsq_f32_e32 v38, v38
	v_pk_fma_f32 v[30:31], v[154:155], v[36:37], v[30:31] op_sel_hi:[1,0,1] neg_lo:[1,0,0] neg_hi:[1,0,0]
	v_pk_fma_f32 v[32:33], v[56:57], v[36:37], v[32:33] op_sel_hi:[1,0,1]
	v_pk_fma_f32 v[26:27], v[36:37], v[146:147], v[26:27] op_sel_hi:[0,1,1] neg_lo:[1,0,0] neg_hi:[1,0,0]
	v_pk_fma_f32 v[28:29], v[36:37], v[148:149], v[28:29] op_sel_hi:[0,1,1] neg_lo:[1,0,0] neg_hi:[1,0,0]
	v_lshl_add_u64 v[34:35], v[34:35], 0, v[178:179]
	v_pk_fma_f32 v[32:33], v[32:33], v[38:39], v[160:161] op_sel_hi:[1,0,1]
	v_pk_fma_f32 v[30:31], v[30:31], v[38:39], v[158:159] op_sel_hi:[1,0,1]
	v_pk_fma_f32 v[40:41], v[28:29], v[38:39], v[152:153] op_sel_hi:[1,0,1]
	v_pk_fma_f32 v[28:29], v[26:27], v[38:39], v[150:151] op_sel_hi:[1,0,1]
; __device__ __forceinline__ unsigned cvt_pk_bf16(float lo, float hi) { unsigned r; asm volatile("v_cvt_pk_bf16_f32 %0, %1, %2" : "=v"(r) : "v"(lo), "v"(hi)); return r; }
; __device__ __forceinline__ void stats_mr(const f32x2 s, float& mu, float& r) { mu = s.x * (1.0f / 1024.0f); const float var = s.y * (1.0f / 1024.0f) - mu * mu; r = __builtin_amdgcn_rsqf(var + 1e-5f); }
; template <class Epi, class Sched, bool ALIGN_EPI = false, bool SP2 = false>
; __device__ __forceinline__ void gemm_phase(PG8_LAS unsigned char* lds, const Gemm g, const Sched& S, const Epi& E) {
;     ...
;         for (int a = 0; a < 2; ++a)
; #pragma unroll
;             for (int b = 0; b < 2; ++b)
; #pragma unroll
;                 for (int m = 0; m < 4; ++m)
; #pragma unroll
;                     for (int n = 0; n < 2; ++n) acc[a][b][m][n] = (f32x4){0.f, 0.f, 0.f, 0.f};
;     __device__ __forceinline__ void operator()(const f32x4 (&acc)[2][2][4][2], const Unit& u, int wr, int wc, int fr, int fq) const {
;     ...
;         for (int ai = 0; ai < 2; ++ai)
; #pragma unroll
;             for (int m = 0; m < 4; ++m) { const int row = row0 + ai * HALF + m * 16; bf16_t* rowp = O + (size_t)row * ldc + col0;
;                 float mu, r; stats_mr(sv[ai][m], mu, r);
; #pragma unroll
;                 for (int bj = 0; bj < 2; ++bj) { const f32x4 v0 = (acc[ai][bj][m][0] - cv[bj][0] * mu) * r + bv[bj][0], v1 = (acc[ai][bj][m][1] - cv[bj][1] * mu) * r + bv[bj][1];
;                     u32x4 w; w.x = cvt_pk_bf16(v0[0], v0[1]); w.y = cvt_pk_bf16(v0[2], v0[3]); w.z = cvt_pk_bf16(v1[0], v1[1]); w.w = cvt_pk_bf16(v1[2], v1[3]);
;                     *(u32x4*)(rowp + bj * HALF) = w; } }
	v_cvt_pk_bf16_f32 v26, v30, v31
	v_mov_b32_e32 v30, 0
	v_mov_b32_e32 v31, 0
	v_cvt_pk_bf16_f32 v27, v32, v33
	v_mov_b32_e32 v32, 0
	v_mov_b32_e32 v33, 0
	v_pk_fma_f32 v[18:19], v[36:37], v[130:131], v[18:19] op_sel_hi:[0,1,1] neg_lo:[1,0,0] neg_hi:[1,0,0]
	v_pk_fma_f32 v[20:21], v[36:37], v[132:133], v[20:21] op_sel_hi:[0,1,1] neg_lo:[1,0,0] neg_hi:[1,0,0]
	v_cvt_pk_bf16_f32 v28, v28, v29
	v_cvt_pk_bf16_f32 v29, v40, v41
	v_mov_b32_e32 v40, 0
	v_mov_b32_e32 v41, 0
	global_store_dwordx4 v[34:35], v[26:29], off
	s_nop 1
	v_mov_b32_e32 v28, 0
	v_mov_b32_e32 v29, 0
	v_pk_fma_f32 v[22:23], v[36:37], v[134:135], v[22:23] op_sel_hi:[0,1,1] neg_lo:[1,0,0] neg_hi:[1,0,0]
	v_pk_fma_f32 v[24:25], v[36:37], v[136:137], v[24:25] op_sel_hi:[0,1,1] neg_lo:[1,0,0] neg_hi:[1,0,0]
	v_mov_b32_e32 v36, 0
	v_mov_b32_e32 v37, 0
	v_pk_fma_f32 v[26:27], v[38:39], v[20:21], v[140:141] op_sel_hi:[0,1,1]
	v_pk_fma_f32 v[20:21], v[38:39], v[18:19], v[138:139] op_sel_hi:[0,1,1]
	v_pk_fma_f32 v[24:25], v[38:39], v[24:25], v[144:145] op_sel_hi:[0,1,1]
	v_pk_fma_f32 v[22:23], v[38:39], v[22:23], v[142:143] op_sel_hi:[0,1,1]
	v_mov_b32_e32 v38, 0
	v_mov_b32_e32 v39, 0
	v_cvt_pk_bf16_f32 v18, v22, v23
	v_cvt_pk_bf16_f32 v19, v24, v25
	v_cvt_pk_bf16_f32 v20, v20, v21
	v_cvt_pk_bf16_f32 v21, v26, v27
	v_mov_b32_e32 v26, 0
	v_mov_b32_e32 v27, 0
	global_store_dwordx4 v[34:35], v[18:21], off offset:256
	s_nop 1
	v_mov_b32_e32 v34, 0
	v_mov_b32_e32 v35, 0
	v_xor_b32_e32 v25, 0x80000000, v149
	v_xor_b32_e32 v24, 0x80000000, v148
	v_pk_mul_f32 v[20:21], v[188:189], s[54:55] op_sel_hi:[1,0]
	v_mad_i64_i32 v[18:19], s[24:25], v176, s69, v[174:175]
	v_fma_f32 v22, -v20, v20, v21
	v_add_f32_e32 v22, 0x3727c5ac, v22
	v_rsq_f32_e32 v22, v22
	v_pk_fma_f32 v[14:15], v[154:155], v[20:21], v[14:15] op_sel_hi:[1,0,1] neg_lo:[1,0,0] neg_hi:[1,0,0]
	v_pk_fma_f32 v[16:17], v[56:57], v[20:21], v[16:17] op_sel_hi:[1,0,1]
	v_mov_b32_e32 v56, 0
	v_mov_b32_e32 v57, 0
	v_pk_fma_f32 v[10:11], v[146:147], v[20:21], v[10:11] op_sel_hi:[1,0,1] neg_lo:[1,0,0] neg_hi:[1,0,0]
	v_pk_fma_f32 v[12:13], v[24:25], v[20:21], v[12:13] op_sel_hi:[1,0,1]
	v_lshl_add_u64 v[18:19], v[18:19], 0, v[178:179]
	v_pk_fma_f32 v[16:17], v[16:17], v[22:23], v[160:161] op_sel_hi:[1,0,1]
	v_pk_fma_f32 v[14:15], v[14:15], v[22:23], v[158:159] op_sel_hi:[1,0,1]
	v_pk_fma_f32 v[24:25], v[12:13], v[22:23], v[152:153] op_sel_hi:[1,0,1]
	v_pk_fma_f32 v[12:13], v[10:11], v[22:23], v[150:151] op_sel_hi:[1,0,1]
	v_cvt_pk_bf16_f32 v10, v14, v15
	v_mov_b32_e32 v14, 0
	v_mov_b32_e32 v15, 0
	v_cvt_pk_bf16_f32 v11, v16, v17
	v_mov_b32_e32 v16, 0
	v_mov_b32_e32 v17, 0
	v_pk_fma_f32 v[2:3], v[20:21], v[130:131], v[2:3] op_sel_hi:[0,1,1] neg_lo:[1,0,0] neg_hi:[1,0,0]
	v_pk_fma_f32 v[4:5], v[20:21], v[132:133], v[4:5] op_sel_hi:[0,1,1] neg_lo:[1,0,0] neg_hi:[1,0,0]
	v_cvt_pk_bf16_f32 v12, v12, v13
	v_cvt_pk_bf16_f32 v13, v24, v25
	v_mov_b32_e32 v24, 0
	v_mov_b32_e32 v25, 0
	global_store_dwordx4 v[18:19], v[10:13], off
	s_nop 1
	v_mov_b32_e32 v12, 0
	v_mov_b32_e32 v13, 0
	v_pk_fma_f32 v[6:7], v[20:21], v[134:135], v[6:7] op_sel_hi:[0,1,1] neg_lo:[1,0,0] neg_hi:[1,0,0]
	v_pk_fma_f32 v[8:9], v[20:21], v[136:137], v[8:9] op_sel_hi:[0,1,1] neg_lo:[1,0,0] neg_hi:[1,0,0]
	v_mov_b32_e32 v20, 0
	v_mov_b32_e32 v21, 0
	v_pk_fma_f32 v[10:11], v[22:23], v[4:5], v[140:141] op_sel_hi:[0,1,1]
	v_pk_fma_f32 v[4:5], v[22:23], v[2:3], v[138:139] op_sel_hi:[0,1,1]
	s_mov_b64 s[24:25], -1
	v_pk_fma_f32 v[8:9], v[8:9], v[22:23], v[144:145] op_sel_hi:[1,0,1]
	v_pk_fma_f32 v[6:7], v[6:7], v[22:23], v[142:143] op_sel_hi:[1,0,1]
	v_mov_b32_e32 v22, 0
	v_mov_b32_e32 v23, 0
	s_nop 0
	v_cvt_pk_bf16_f32 v2, v6, v7
	v_mov_b32_e32 v6, 0
	v_mov_b32_e32 v7, 0
	v_cvt_pk_bf16_f32 v3, v8, v9
	v_mov_b32_e32 v8, 0
	v_mov_b32_e32 v9, 0
	v_cvt_pk_bf16_f32 v4, v4, v5
	v_cvt_pk_bf16_f32 v5, v10, v11
	v_mov_b32_e32 v10, 0
	v_mov_b32_e32 v11, 0
	global_store_dwordx4 v[18:19], v[2:5], off offset:256
	s_nop 1
	v_mov_b32_e32 v4, 0
	v_mov_b32_e32 v5, 0
	v_mov_b32_e32 v18, 0
	v_mov_b32_e32 v19, 0
	s_cbranch_vccnz .LBB0_811
	s_andn2_b64 vcc, exec, s[0:1]
	s_cbranch_vccnz .LBB0_810
	s_barrier
	s_branch .LBB0_810
